# Ph12 up-conv epilogue: coefficient loads hoisted above halo stores with one counted vmcnt(8) (no store-ack waits); attention loop: running staging pointers and precomputed LDS bases (6 fewer VALU per
# speedup vs baseline: 1.0345x; 1.0110x over previous
; #define FL_GLOADK(j) do { \
;     _Pragma("unroll") for (int i_ = 0; i_ < KPT; ++i_) { const int ci = tid + 512 * i_; if (ci < NKC) { const int key = ci / KCH, ch = ci - key * KCH; \
;         kreg[i_] = *(const u32x4*)(K0 + (size_t)(64 * (j) + key) * kpitch + ch * 8); } } } while (0)
; #define FL_LSTOREK(buf) do { \
;     _Pragma("unroll") for (int i_ = 0; i_ < KPT; ++i_) { const int ci = tid + 512 * i_; if (ci < NKC) { const int key = ci / KCH, ch = ci - key * KCH; \
;         *(LAS u32x4*)(lds + (buf) * KB + (key * KP + ch * 8) * 2) = kreg[i_]; } } } while (0)
; #define FL_GLOADV(j) do { \
;     _Pragma("unroll") for (int i_ = 0; i_ < VPT; ++i_) { const int ci = tid + 512 * i_; const int d = ci >> 3, ch = ci & 7; kreg[i_] = *(const u32x4*)(VT + (size_t)d * vpitch + 64 * (j) + ch * 8); } } while (0)
; #define FL_LSTOREV(buf) do { \
;     _Pragma("unroll") for (int i_ = 0; i_ < VPT; ++i_) { const int ci = tid + 512 * i_; const int d = ci >> 3, ch = ci & 7; LAS u32x2* p_ = (LAS u32x2*)(lds + 2 * KB + (buf) * VB + (d * VP + ch * 8) * 2); \
;         p_[0] = (u32x2){kreg[i_].x, kreg[i_].y}; p_[1] = (u32x2){kreg[i_].z, kreg[i_].w}; } } while (0)
; template <int DQK, int DV, int MODE>
; __device__ __forceinline__ void flash_unit(LAS unsigned char* lds, const bf16* Qp, int qpitch, const bf16* K0, int kpitch, const bf16* K1, const bf16* VT, int vpitch,
;                                            bf16* Op, int opitch, int NT, int jbase, int qpos0) {
;     ...
;     for (int j = 0; j < NT; ++j) {
;         const int buf = j & 1;
;         if (j + 1 < NT) { if constexpr (MODE == 1) { FL_GLOADK(j + 1); FL_LSTOREK(buf ^ 1); FL_GLOADV(j + 1); FL_LSTOREV(buf ^ 1); } else { FL_GLOAD(j + 1); } }
;         if (MODE == 1 || j <= jmax) { FL_X(j); FL_Y(j); }
;         if constexpr (MODE == 0) { if (j + 1 < NT) { FL_LSTORE(buf ^ 1); } }
;         __syncthreads();
.LBB0_548:
	s_or_b64 exec, exec, s[6:7]
	v_add_u32_e32 v160, v90, v87
	v_mad_u64_u32 v[2:3], s[6:7], v160, -12, v[84:85]
	v_add_u32_e32 v0, 0x8a00, v155
	v_lshlrev_b32_e32 v4, 3, v2
	v_mad_u64_u32 v[8:9], s[6:7], v14, -12, v[86:87]
	s_waitcnt vmcnt(0) lgkmcnt(0)
	ds_write2_b64 v0, v[64:65], v[66:67] offset1:1
	v_ashrrev_i32_e32 v5, 31, v4
	v_subrev_u32_e32 v0, 64, v4
	v_lshlrev_b32_e32 v10, 3, v8
	v_lshl_add_u64 v[6:7], v[4:5], 1, s[14:15]
	v_lshl_add_u64 v[4:5], v[0:1], 1, s[16:17]
	v_ashrrev_i32_e32 v11, 31, v10
	v_subrev_u32_e32 v0, 64, v10
	v_lshl_add_u64 v[12:13], v[10:11], 1, s[14:15]
	v_lshl_add_u64 v[10:11], v[0:1], 1, s[16:17]
	v_and_b32_e32 v0, 7, v85
	v_cmp_lt_i32_e32 vcc, 7, v2
	v_lshlrev_b32_e32 v0, 4, v0
	v_lshlrev_b32_e32 v178, 4, v2
	v_cndmask_b32_e32 v167, v7, v5, vcc
	v_cndmask_b32_e32 v166, v6, v4, vcc
	v_cndmask_b32_e64 v168, 10, 6, vcc
	v_cmp_lt_i32_e32 vcc, 7, v8
	v_ashrrev_i32_e32 v161, 31, v160
	v_ashrrev_i32_e32 v15, 31, v14
	v_lshl_add_u64 v[2:3], v[88:89], 0, v[0:1]
	v_mul_lo_u32 v179, v160, s49
	v_cndmask_b32_e32 v163, v13, v11, vcc
	v_cndmask_b32_e32 v162, v12, v10, vcc
	v_cndmask_b32_e64 v164, 10, 6, vcc
	v_lshl_add_u64 v[170:171], v[160:161], 0, s[10:11]
	v_lshl_add_u64 v[172:173], v[14:15], 0, s[10:11]
	v_lshl_add_u64 v[174:175], s[20:21], 0, v[2:3]
	v_lshlrev_b64 v[232:233], v168, v[170:171]
	v_lshl_add_u64 v[232:233], v[166:167], 0, v[232:233]
	v_lshlrev_b64 v[234:235], v164, v[172:173]
	v_lshl_add_u64 v[234:235], v[162:163], 0, v[234:235]
	v_mov_b32_e32 v236, 64
	v_mov_b32_e32 v237, 0
	v_lshlrev_b64 v[238:239], v164, v[236:237]
	v_lshlrev_b64 v[236:237], v168, v[236:237]
	v_add_u32_e32 v240, 0x6800, v155
	v_add_u32_e32 v241, 0x6800, v165
	v_add_u32_e32 v242, 0x7800, v165
	s_mov_b32 s64, -2
	s_waitcnt lgkmcnt(0)
	s_barrier
	s_branch .LBB0_550
.LBB0_549:
	s_or_b64 exec, exec, s[6:7]
	s_mulk_i32 s8, 0x2200
	v_add_u32_e32 v0, s8, v240
	s_add_i32 s64, s64, 1
	v_lshl_add_u64 v[232:233], v[232:233], 0, v[236:237]
	v_lshl_add_u64 v[234:235], v[234:235], 0, v[238:239]
	s_cmp_lg_u32 s27, s64
	v_lshl_add_u64 v[174:175], v[174:175], 0, s[10:11]
	s_waitcnt vmcnt(0) lgkmcnt(0)
	ds_write2_b64 v0, v[2:3], v[4:5] offset1:1
	s_waitcnt lgkmcnt(0)
	s_barrier
	s_cbranch_scc0 .LBB0_562
.LBB0_550:
	s_and_saveexec_b64 s[6:7], s[2:3]
	s_cbranch_execz .LBB0_552
	global_load_dwordx4 v[96:99], v[232:233], off
.LBB0_552:
	s_or_b64 exec, exec, s[6:7]
	s_and_saveexec_b64 s[6:7], s[4:5]
	s_cbranch_execz .LBB0_554
	global_load_dwordx4 v[100:103], v[234:235], off
.LBB0_554:
	s_or_b64 exec, exec, s[6:7]
	global_load_dwordx4 v[2:5], v[174:175], off
	s_add_i32 s7, s64, 3
	s_and_b32 s6, s7, 1
	s_cmp_gt_i32 s7, s26
	s_cbranch_scc1 .LBB0_558
	s_mul_i32 s7, s6, 0x3400
	v_add_u32_e32 v0, s7, v169
	ds_read_b128 v[6:9], v0
	ds_read_b128 v[10:13], v0 offset:32
	ds_read_b128 v[128:131], v0 offset:6656
	ds_read_b128 v[132:135], v0 offset:6688
	ds_read_b128 v[136:139], v0 offset:64
	ds_read_b128 v[140:143], v0 offset:96
	ds_read_b128 v[144:147], v0 offset:6720
	ds_read_b128 v[148:151], v0 offset:6752
	ds_read_b128 v[180:183], v0 offset:128
	ds_read_b128 v[184:187], v0 offset:160
	ds_read_b128 v[188:191], v0 offset:6784
	ds_read_b128 v[192:195], v0 offset:6816
	s_waitcnt lgkmcnt(8)
	v_mfma_f32_32x32x16_bf16 v[80:95], v[6:9], v[116:119], v[48:63]
	v_mfma_f32_32x32x16_bf16 v[64:79], v[128:131], v[116:119], v[48:63]
	v_mfma_f32_32x32x16_bf16 v[80:95], v[10:13], v[112:115], v[80:95]
	v_mfma_f32_32x32x16_bf16 v[64:79], v[132:135], v[112:115], v[64:79]
	s_waitcnt lgkmcnt(4)
	v_mfma_f32_32x32x16_bf16 v[80:95], v[136:139], v[108:111], v[80:95]
	v_mfma_f32_32x32x16_bf16 v[64:79], v[144:147], v[108:111], v[64:79]
	v_mfma_f32_32x32x16_bf16 v[80:95], v[140:143], v[104:107], v[80:95]
	v_mfma_f32_32x32x16_bf16 v[64:79], v[148:151], v[104:107], v[64:79]
	s_waitcnt lgkmcnt(0)
	v_mfma_f32_32x32x16_bf16 v[80:95], v[180:183], v[120:123], v[80:95]
	v_mfma_f32_32x32x16_bf16 v[64:79], v[188:191], v[120:123], v[64:79]
	v_mfma_f32_32x32x16_bf16 v[80:95], v[184:187], v[124:127], v[80:95]
	v_mfma_f32_32x32x16_bf16 v[64:79], v[192:195], v[124:127], v[64:79]
	s_mul_i32 s7, s6, 0x2200
	v_add_u32_e32 v6, s7, v241
	v_add_u32_e32 v0, s7, v242
	ds_read2_b64 v[148:151], v6 offset1:2
	ds_read2_b64 v[144:147], v6 offset0:4 offset1:6
	ds_read2_b64 v[140:143], v6 offset0:8 offset1:10
	ds_read2_b64 v[136:139], v6 offset0:12 offset1:14
	ds_read2_b64 v[132:135], v0 offset0:32 offset1:34
	ds_read2_b64 v[128:131], v0 offset0:36 offset1:38
	ds_read2_b64 v[10:13], v0 offset0:40 offset1:42
	ds_read2_b64 v[6:9], v0 offset0:44 offset1:46

; __device__ __forceinline__ unsigned pk2(float lo, float hi) { const f32x2 v = {lo, hi}; return __builtin_bit_cast(unsigned, __builtin_convertvector(v, bf16x2_t)); }
;     __device__ __forceinline__ void operator()(f32x4 (&acc)[2][2][4][2], const Unit& u, int, int, int, int) const {
;         const int tid = my_tid(lds), wid = __builtin_amdgcn_readfirstlane(tid >> 6), lane = tid & 63, wr = wid >> 2, wc = wid & 3, fr = lane & 15, fq = lane >> 4;
;         const int f0 = u.pn * 128 + wc * 32 + 8 * fq, rowt = u.pm * BM + wr * 64 + fr;
; #pragma unroll
;         for (int ai = 0; ai < 2; ++ai) { const int gidx = u.pm * 4 + ai * 2 + wr;
;             if (fr < 2) { bf16* h = HB + (size_t)(gidx * 4 + fr) * NUP + f0;
; #pragma unroll
;                 for (int bj = 0; bj < 2; ++bj) { const f32x4 v0 = acc[ai][bj][0][0], v1 = acc[ai][bj][0][1]; u32x4 w; w.x = pk2(v0[0], v0[1]); w.y = pk2(v0[2], v0[3]); w.z = pk2(v1[0], v1[1]); w.w = pk2(v1[2], v1[3]); *(u32x4*)(h + bj * NFF) = w; } }
;             if (fr >= 14) { bf16* h = HB + (size_t)(gidx * 4 + 2 + (fr - 14)) * NUP + f0; const int R = rowt + ai * HALF + 48, t = R & (SEQ - 1);
;                 float* co = (t >= SEQ - 2) ? out + O_PCONV + (size_t)((R >> 14) * 2 + (t - (SEQ - 2))) * NUP + f0 : nullptr;
; #pragma unroll
;                 for (int bj = 0; bj < 2; ++bj) { const f32x4 v0 = acc[ai][bj][3][0], v1 = acc[ai][bj][3][1]; u32x4 w; w.x = pk2(v0[0], v0[1]); w.y = pk2(v0[2], v0[3]); w.z = pk2(v1[0], v1[1]); w.w = pk2(v1[2], v1[3]); *(u32x4*)(h + bj * NFF) = w;
;                     if (co) { *(f32x4*)(co + bj * NFF) = v0; *(f32x4*)(co + bj * NFF + 4) = v1; } } }
;         }
;         __builtin_amdgcn_sched_barrier(0);
;         f32x4 wa0[2], wa1[2], wa2[2], ba[2], wg0[2], wg1[2], wg2[2], bg[2];
; #pragma unroll
;         for (int n = 0; n < 2; ++n) { const int ch = f0 + 4 * n;
;             wa0[n] = *(const f32x4*)(cw + ch); wa1[n] = *(const f32x4*)(cw + NUP + ch); wa2[n] = *(const f32x4*)(cw + 2 * NUP + ch); ba[n] = *(const f32x4*)(cb + ch);
;             wg0[n] = *(const f32x4*)(cw + NFF + ch); wg1[n] = *(const f32x4*)(cw + NUP + NFF + ch); wg2[n] = *(const f32x4*)(cw + 2 * NUP + NFF + ch); bg[n] = *(const f32x4*)(cb + NFF + ch); }
.LBB0_1448:
	s_getreg_b32 s7, hwreg(HW_REG_HW_ID, 0, 6)
	s_lshl_b32 s7, s7, 2
	s_and_b32 s7, s7, 0xfc
	s_add_i32 s7, s7, 0
	s_add_i32 s7, s7, 0x25a00
	v_mov_b32_e32 v228, s7
	ds_read_b32 v228, v228
	v_mbcnt_lo_u32_b32 v229, -1, 0
	v_mbcnt_hi_u32_b32 v229, -1, v229
	s_lshl_b32 s6, s6, 7
	v_and_b32_e32 v233, 15, v229
	s_lshl_b32 s12, s10, 2
	s_waitcnt lgkmcnt(0)
	v_readfirstlane_b32 s7, v228
	v_cmp_gt_u32_e64 s[8:9], 2, v233
	s_nop 0
	v_lshl_add_u32 v228, s7, 6, v229
	s_nop 0
	v_readfirstlane_b32 s7, v228
	s_ashr_i32 s11, s7, 8
	s_lshr_b32 s7, s7, 1
	s_and_b32 s7, s7, 0x60
	s_or_b32 s6, s7, s6
	v_lshrrev_b32_e32 v228, 1, v229
	v_and_or_b32 v208, v228, 24, s6
	v_cmp_lt_u32_e64 s[6:7], 1, v233
	v_ashrrev_i32_e32 v209, 31, v208
	v_lshlrev_b64 v[84:85], 2, v[208:209]
	v_lshl_add_u64 v[88:89], s[30:31], 0, v[84:85]
	v_lshl_add_u64 v[90:91], s[34:35], 0, v[84:85]
	global_load_dwordx4 v[148:151], v[88:89], off
	global_load_dwordx4 v[144:147], v[90:91], off
	v_lshl_add_u64 v[90:91], s[38:39], 0, v[84:85]
	v_lshl_add_u64 v[86:87], s[14:15], 0, v[84:85]
	v_lshl_add_u64 v[88:89], s[16:17], 0, v[84:85]
	v_lshl_add_u64 v[92:93], s[40:41], 0, v[84:85]
	global_load_dwordx4 v[128:131], v[90:91], off
	global_load_dwordx4 v[132:135], v[92:93], off
	v_lshl_add_u64 v[90:91], s[42:43], 0, v[84:85]
	v_lshl_add_u64 v[84:85], s[46:47], 0, v[84:85]
	global_load_dwordx4 v[140:143], v[84:85], off
	v_or_b32_e32 v84, 4, v208
	v_ashrrev_i32_e32 v85, 31, v84
	v_lshlrev_b64 v[96:97], 2, v[84:85]
	v_lshl_add_u64 v[84:85], s[30:31], 0, v[96:97]
	global_load_dwordx4 v[136:139], v[90:91], off
	global_load_dwordx4 v[152:155], v[86:87], off
	global_load_dwordx4 v[100:103], v[86:87], off offset:16
	v_lshl_add_u64 v[86:87], s[34:35], 0, v[96:97]
	global_load_dwordx4 v[108:111], v[84:85], off
	global_load_dwordx4 v[104:107], v[86:87], off
	global_load_dwordx4 v[156:159], v[88:89], off
	global_load_dwordx4 v[112:115], v[88:89], off offset:16
	v_lshl_add_u64 v[84:85], s[38:39], 0, v[96:97]
	v_lshl_add_u64 v[88:89], s[40:41], 0, v[96:97]
	v_lshl_add_u64 v[92:93], s[42:43], 0, v[96:97]
	v_lshl_add_u64 v[96:97], s[46:47], 0, v[96:97]
	global_load_dwordx4 v[84:87], v[84:85], off
	s_nop 0
	global_load_dwordx4 v[88:91], v[88:89], off
	global_load_dwordx4 v[92:95], v[92:93], off
	global_load_dwordx4 v[96:99], v[96:97], off
	s_add_i32 s49, s11, s12
	s_and_saveexec_b64 s[12:13], s[8:9]
	s_cbranch_execz .LBB0_1450
	v_lshl_or_b32 v230, s49, 2, v233
	v_mov_b64_e32 v[228:229], s[22:23]
	v_mad_i64_i32 v[228:229], s[52:53], v230, s80, v[228:229]
	v_lshl_add_u64 v[234:235], v[208:209], 1, v[228:229]
	v_cvt_pk_bf16_f32 v228, v188, v189
	v_cvt_pk_bf16_f32 v229, v190, v191
	v_cvt_pk_bf16_f32 v230, v180, v181
	v_cvt_pk_bf16_f32 v231, v182, v183
	global_store_dwordx4 v[234:235], v[228:231], off
	v_add_co_u32_e32 v234, vcc, 0x1000, v234
	s_nop 0
	v_cvt_pk_bf16_f32 v228, v184, v185
	v_cvt_pk_bf16_f32 v229, v186, v187
	v_cvt_pk_bf16_f32 v230, v176, v177
	v_cvt_pk_bf16_f32 v231, v178, v179
	v_addc_co_u32_e32 v235, vcc, 0, v235, vcc
	global_store_dwordx4 v[234:235], v[228:231], off offset:1536
.LBB0_1450:
	s_or_b64 exec, exec, s[12:13]
	s_lshl_b32 s10, s10, 8
	s_lshl_b32 s51, s11, 6
	s_add_i32 s51, s51, s10
	v_or_b32_e32 v246, s51, v233
	v_cmp_lt_u32_e64 s[10:11], 13, v233
	v_add_u32_e32 v232, -12, v233
	s_and_saveexec_b64 s[58:59], s[10:11]
	s_cbranch_execz .LBB0_1457
	v_and_b32_e32 v230, 0x3fcf, v246
	v_cmp_lt_u32_e32 vcc, s81, v230
	v_mov_b64_e32 v[228:229], 0
	s_and_saveexec_b64 s[12:13], vcc
	s_ashr_i32 s51, s51, 13
	s_and_b32 s51, s51, 0xfffffe
	v_add_u32_e32 v228, s51, v230
	v_add_u32_e32 v228, 0xffffc032, v228
	v_mul_hi_i32_i24_e32 v229, 0x5800, v228
	v_mul_i32_i24_e32 v228, 0x5800, v228
	v_lshl_add_u64 v[228:229], s[28:29], 0, v[228:229]
	v_lshl_add_u64 v[228:229], v[208:209], 2, v[228:229]
	s_or_b64 exec, exec, s[12:13]
	v_lshl_add_u32 v234, s49, 2, v232
	v_mov_b64_e32 v[230:231], s[22:23]
	v_mad_i64_i32 v[230:231], s[12:13], v234, s80, v[230:231]
	v_lshl_add_u64 v[230:231], v[208:209], 1, v[230:231]
	v_cmp_ne_u64_e64 s[12:13], 0, v[228:229]
	v_cvt_pk_bf16_f32 v234, v120, v121
	v_cvt_pk_bf16_f32 v235, v122, v123
	v_cvt_pk_bf16_f32 v236, v72, v73
	v_cvt_pk_bf16_f32 v237, v74, v75
	global_store_dwordx4 v[230:231], v[234:237], off
	s_and_saveexec_b64 s[60:61], s[12:13]
	s_cbranch_execz .LBB0_1455
	global_store_dwordx4 v[228:229], v[120:123], off
	global_store_dwordx4 v[228:229], v[72:75], off offset:16
.LBB0_1455:
	s_or_b64 exec, exec, s[60:61]
	v_add_co_u32_e32 v230, vcc, 0x1000, v230
	v_cvt_pk_bf16_f32 v234, v80, v81
	v_cvt_pk_bf16_f32 v235, v82, v83
	v_cvt_pk_bf16_f32 v236, v64, v65
	v_cvt_pk_bf16_f32 v237, v66, v67
	v_addc_co_u32_e32 v231, vcc, 0, v231, vcc
	global_store_dwordx4 v[230:231], v[234:237], off offset:1536
	s_and_b64 exec, exec, s[12:13]
	s_cbranch_execz .LBB0_1457
	v_add_co_u32_e32 v228, vcc, 0x2000, v228
	s_nop 1
	v_addc_co_u32_e32 v229, vcc, 0, v229, vcc
	global_store_dwordx4 v[228:229], v[80:83], off offset:3072
	global_store_dwordx4 v[228:229], v[64:67], off offset:3088
.LBB0_1457:
	s_or_b64 exec, exec, s[58:59]
	s_add_i32 s49, s49, 2
	s_and_saveexec_b64 s[12:13], s[8:9]
	s_cbranch_execz .LBB0_1459
	v_lshl_or_b32 v230, s49, 2, v233
	v_mov_b64_e32 v[228:229], s[22:23]
	v_mad_i64_i32 v[228:229], s[8:9], v230, s80, v[228:229]
	v_lshl_add_u64 v[234:235], v[208:209], 1, v[228:229]
	v_cvt_pk_bf16_f32 v228, v60, v61
	v_cvt_pk_bf16_f32 v229, v62, v63
	v_cvt_pk_bf16_f32 v230, v52, v53
	v_cvt_pk_bf16_f32 v231, v54, v55
	global_store_dwordx4 v[234:235], v[228:231], off
	v_add_co_u32_e32 v234, vcc, 0x1000, v234
	s_nop 0
	v_cvt_pk_bf16_f32 v228, v56, v57
	v_cvt_pk_bf16_f32 v229, v58, v59
	v_cvt_pk_bf16_f32 v230, v48, v49
	v_cvt_pk_bf16_f32 v231, v50, v51
	v_addc_co_u32_e32 v235, vcc, 0, v235, vcc
	global_store_dwordx4 v[234:235], v[228:231], off offset:1536
; __device__ __forceinline__ unsigned pk2(float lo, float hi) { const f32x2 v = {lo, hi}; return __builtin_bit_cast(unsigned, __builtin_convertvector(v, bf16x2_t)); }
;     __device__ __forceinline__ void operator()(f32x4 (&acc)[2][2][4][2], const Unit& u, int, int, int, int) const {
;     ...
;         for (int ai = 0; ai < 2; ++ai) { const int gidx = u.pm * 4 + ai * 2 + wr;
;             if (fr < 2) { bf16* h = HB + (size_t)(gidx * 4 + fr) * NUP + f0;
; #pragma unroll
;                 for (int bj = 0; bj < 2; ++bj) { const f32x4 v0 = acc[ai][bj][0][0], v1 = acc[ai][bj][0][1]; u32x4 w; w.x = pk2(v0[0], v0[1]); w.y = pk2(v0[2], v0[3]); w.z = pk2(v1[0], v1[1]); w.w = pk2(v1[2], v1[3]); *(u32x4*)(h + bj * NFF) = w; } }
;             if (fr >= 14) { bf16* h = HB + (size_t)(gidx * 4 + 2 + (fr - 14)) * NUP + f0; const int R = rowt + ai * HALF + 48, t = R & (SEQ - 1);
;                 float* co = (t >= SEQ - 2) ? out + O_PCONV + (size_t)((R >> 14) * 2 + (t - (SEQ - 2))) * NUP + f0 : nullptr;
; #pragma unroll
;                 for (int bj = 0; bj < 2; ++bj) { const f32x4 v0 = acc[ai][bj][3][0], v1 = acc[ai][bj][3][1]; u32x4 w; w.x = pk2(v0[0], v0[1]); w.y = pk2(v0[2], v0[3]); w.z = pk2(v1[0], v1[1]); w.w = pk2(v1[2], v1[3]); *(u32x4*)(h + bj * NFF) = w;
;                     if (co) { *(f32x4*)(co + bj * NFF) = v0; *(f32x4*)(co + bj * NFF + 4) = v1; } } }
;     ...
;                     for (int e = 0; e < 4; ++e) { const float A = acc[ai][0][m][n][e], Gv = acc[ai][1][m][n][e];
;                         const float Ap = m > 0 ? acc[ai][0][m > 0 ? m - 1 : 0][n][e] : 0.f, Gp = m > 0 ? acc[ai][1][m > 0 ? m - 1 : 0][n][e] : 0.f;
;                         const float a1 = dpp_prev(A, Ap, 1), a2 = dpp_prev(A, Ap, 2), g1 = dpp_prev(Gv, Gp, 1), g2 = dpp_prev(Gv, Gp, 2);
.LBB0_1459:
	s_or_b64 exec, exec, s[12:13]
	v_add_u32_e32 v247, 0x80, v246
	s_and_saveexec_b64 s[12:13], s[10:11]
	s_cbranch_execz .LBB0_1466
	v_and_b32_e32 v230, 0x3fcf, v247
	v_cmp_lt_u32_e32 vcc, s81, v230
	v_mov_b64_e32 v[228:229], 0
	s_and_saveexec_b64 s[8:9], vcc
	v_ashrrev_i32_e32 v228, 13, v247
	v_and_b32_e32 v228, 0xfffffe, v228
	v_add3_u32 v228, v230, v228, s82
	v_mul_hi_i32_i24_e32 v229, 0x5800, v228
	v_mul_i32_i24_e32 v228, 0x5800, v228
	v_lshl_add_u64 v[228:229], s[28:29], 0, v[228:229]
	v_lshl_add_u64 v[228:229], v[208:209], 2, v[228:229]
	s_or_b64 exec, exec, s[8:9]
	v_lshl_add_u32 v232, s49, 2, v232
	v_mov_b64_e32 v[230:231], s[22:23]
	v_mad_i64_i32 v[230:231], s[8:9], v232, s80, v[230:231]
	v_lshl_add_u64 v[230:231], v[208:209], 1, v[230:231]
	v_cmp_ne_u64_e64 s[8:9], 0, v[228:229]
	v_cvt_pk_bf16_f32 v232, v24, v25
	v_cvt_pk_bf16_f32 v233, v26, v27
	v_cvt_pk_bf16_f32 v234, v8, v9
	v_cvt_pk_bf16_f32 v235, v10, v11
	global_store_dwordx4 v[230:231], v[232:235], off
	s_and_saveexec_b64 s[10:11], s[8:9]
	s_cbranch_execz .LBB0_1464
	global_store_dwordx4 v[228:229], v[24:27], off
	global_store_dwordx4 v[228:229], v[8:11], off offset:16
.LBB0_1464:
	s_or_b64 exec, exec, s[10:11]
	v_add_co_u32_e32 v230, vcc, 0x1000, v230
	v_cvt_pk_bf16_f32 v232, v16, v17
	v_cvt_pk_bf16_f32 v233, v18, v19
	v_cvt_pk_bf16_f32 v234, v0, v1
	v_cvt_pk_bf16_f32 v235, v2, v3
	v_addc_co_u32_e32 v231, vcc, 0, v231, vcc
	global_store_dwordx4 v[230:231], v[232:235], off offset:1536
	s_and_b64 exec, exec, s[8:9]
	s_cbranch_execz .LBB0_1466
	v_add_co_u32_e32 v228, vcc, 0x2000, v228
	s_nop 1
	v_addc_co_u32_e32 v229, vcc, 0, v229, vcc
	global_store_dwordx4 v[228:229], v[16:19], off offset:3072
	global_store_dwordx4 v[228:229], v[0:3], off offset:3088
.LBB0_1466:
	s_or_b64 exec, exec, s[12:13]
	v_mov_b32_dpp v211, v195 row_ror:1 row_mask:0xf bank_mask:0xf bound_ctrl:1
	v_mov_b32_dpp v213, v195 row_ror:2 row_mask:0xf bank_mask:0xf bound_ctrl:1
	v_mov_b32_e32 v218, v211
	v_mov_b32_e32 v220, v213
	v_mov_b32_e32 v214, v211
	v_mov_b32_e32 v216, v213
	v_mov_b32_e32 v219, v211
	v_mov_b32_e32 v221, v213
	v_mov_b32_e32 v215, v211
	v_mov_b32_e32 v217, v213
	v_mov_b32_e32 v230, v211
	v_mov_b32_e32 v232, v213
	v_mov_b32_e32 v226, v211
	v_mov_b32_e32 v228, v213
	v_mov_b32_e32 v231, v211
	v_mov_b32_e32 v233, v213
	v_mov_b32_e32 v227, v211
	v_mov_b32_e32 v229, v213
	v_mov_b32_e32 v238, v211
	v_mov_b32_e32 v240, v213
	v_mov_b32_e32 v234, v211
	v_mov_b32_e32 v236, v213
	v_mov_b32_e32 v239, v211
	v_mov_b32_e32 v241, v213
	v_mov_b32_e32 v235, v211
	v_mov_b32_e32 v237, v213
	v_mov_b32_e32 v222, v211
	v_mov_b32_e32 v224, v213
	v_mov_b32_e32 v210, v211
	v_mov_b32_e32 v212, v213
	v_mov_b32_e32 v223, v211
	v_mov_b32_e32 v225, v213
	v_mov_b32_dpp v218, v188 row_shr:1 row_mask:0xf bank_mask:0xf
	v_mov_b32_dpp v220, v188 row_shr:2 row_mask:0xf bank_mask:0xf
	v_mov_b32_dpp v214, v184 row_shr:1 row_mask:0xf bank_mask:0xf
	v_mov_b32_dpp v216, v184 row_shr:2 row_mask:0xf bank_mask:0xf
	v_mov_b32_dpp v219, v189 row_shr:1 row_mask:0xf bank_mask:0xf
	v_mov_b32_dpp v221, v189 row_shr:2 row_mask:0xf bank_mask:0xf
	v_mov_b32_dpp v215, v185 row_shr:1 row_mask:0xf bank_mask:0xf
	v_mov_b32_dpp v217, v185 row_shr:2 row_mask:0xf bank_mask:0xf
	v_mov_b32_dpp v230, v190 row_shr:1 row_mask:0xf bank_mask:0xf
	v_mov_b32_dpp v232, v190 row_shr:2 row_mask:0xf bank_mask:0xf
	v_mov_b32_dpp v226, v186 row_shr:1 row_mask:0xf bank_mask:0xf
	v_mov_b32_dpp v228, v186 row_shr:2 row_mask:0xf bank_mask:0xf
	v_mov_b32_dpp v231, v191 row_shr:1 row_mask:0xf bank_mask:0xf
	v_mov_b32_dpp v233, v191 row_shr:2 row_mask:0xf bank_mask:0xf
	v_mov_b32_dpp v227, v187 row_shr:1 row_mask:0xf bank_mask:0xf
	v_mov_b32_dpp v229, v187 row_shr:2 row_mask:0xf bank_mask:0xf
	v_mov_b32_dpp v238, v180 row_shr:1 row_mask:0xf bank_mask:0xf
	v_mov_b32_dpp v240, v180 row_shr:2 row_mask:0xf bank_mask:0xf
	v_mov_b32_dpp v234, v176 row_shr:1 row_mask:0xf bank_mask:0xf
	v_mov_b32_dpp v236, v176 row_shr:2 row_mask:0xf bank_mask:0xf
	v_mov_b32_dpp v239, v181 row_shr:1 row_mask:0xf bank_mask:0xf
	v_mov_b32_dpp v241, v181 row_shr:2 row_mask:0xf bank_mask:0xf
	v_mov_b32_dpp v235, v177 row_shr:1 row_mask:0xf bank_mask:0xf
	v_mov_b32_dpp v237, v177 row_shr:2 row_mask:0xf bank_mask:0xf
	v_mov_b32_dpp v222, v182 row_shr:1 row_mask:0xf bank_mask:0xf
	v_mov_b32_dpp v224, v182 row_shr:2 row_mask:0xf bank_mask:0xf
	v_mov_b32_dpp v210, v178 row_shr:1 row_mask:0xf bank_mask:0xf
	v_mov_b32_dpp v212, v178 row_shr:2 row_mask:0xf bank_mask:0xf
	v_mov_b32_dpp v223, v183 row_shr:1 row_mask:0xf bank_mask:0xf
	v_mov_b32_dpp v225, v183 row_shr:2 row_mask:0xf bank_mask:0xf
	v_mov_b32_dpp v211, v179 row_shr:1 row_mask:0xf bank_mask:0xf
	v_mov_b32_dpp v213, v179 row_shr:2 row_mask:0xf bank_mask:0xf
	s_waitcnt vmcnt(8) lgkmcnt(0)
	s_and_saveexec_b64 s[8:9], s[6:7]
	s_xor_b64 s[8:9], exec, s[8:9]
	s_cbranch_execz .LBB0_1468
; __device__ __forceinline__ unsigned pk2(float lo, float hi) { const f32x2 v = {lo, hi}; return __builtin_bit_cast(unsigned, __builtin_convertvector(v, bf16x2_t)); }
; __device__ __forceinline__ float silu(float x) { return x * __builtin_amdgcn_rcpf(1.f + __builtin_amdgcn_exp2f(-1.4426950408889634f * x)); }
;     __device__ __forceinline__ void operator()(f32x4 (&acc)[2][2][4][2], const Unit& u, int, int, int, int) const {
;     ...
;             for (int m = 0; m < 4; ++m) { float r[8];
; #pragma unroll
;                 for (int n = 0; n < 2; ++n)
; #pragma unroll
;                     for (int e = 0; e < 4; ++e) { const float A = acc[ai][0][m][n][e], Gv = acc[ai][1][m][n][e];
;                         const float Ap = m > 0 ? acc[ai][0][m > 0 ? m - 1 : 0][n][e] : 0.f, Gp = m > 0 ? acc[ai][1][m > 0 ? m - 1 : 0][n][e] : 0.f;
;                         const float a1 = dpp_prev(A, Ap, 1), a2 = dpp_prev(A, Ap, 2), g1 = dpp_prev(Gv, Gp, 1), g2 = dpp_prev(Gv, Gp, 2);
;                         const float ca = ba[n][e] + wa0[n][e] * a2 + wa1[n][e] * a1 + wa2[n][e] * A, cg = bg[n][e] + wg0[n][e] * g2 + wg1[n][e] * g1 + wg2[n][e] * Gv;
;                         r[4 * n + e] = silu(ca) * cg; }
;                 if (!(m == 0 && fr < 2)) { u32x4 w; w.x = pk2(r[0], r[1]); w.y = pk2(r[2], r[3]); w.z = pk2(r[4], r[5]); w.w = pk2(r[6], r[7]);
;                     *(u32x4*)(ACT + (size_t)(rowt + ai * HALF + m * 16) * NFF + f0) = w; }
	v_pk_fma_f32 v[240:241], v[100:101], v[240:241], v[112:113]
	v_pk_fma_f32 v[232:233], v[154:155], v[232:233], v[158:159]
	v_pk_fma_f32 v[238:239], v[108:109], v[238:239], v[240:241]
	v_pk_fma_f32 v[230:231], v[150:151], v[230:231], v[232:233]
	v_pk_fma_f32 v[238:239], v[180:181], v[104:105], v[238:239]
	v_pk_fma_f32 v[230:231], v[190:191], v[146:147], v[230:231]
	v_mul_f32_e32 v240, 0xbfb8aa3b, v238
	v_mul_f32_e32 v241, 0xbfb8aa3b, v239
	v_exp_f32_e32 v240, v240
	v_exp_f32_e32 v241, v241
	v_pk_fma_f32 v[236:237], v[84:85], v[236:237], v[96:97]
	v_mul_f32_e32 v232, 0xbfb8aa3b, v230
	v_add_f32_e32 v240, 1.0, v240
	v_add_f32_e32 v241, 1.0, v241
	v_rcp_f32_e32 v240, v240
	v_rcp_f32_e32 v241, v241
	v_pk_fma_f32 v[234:235], v[88:89], v[234:235], v[236:237]
	v_pk_fma_f32 v[220:221], v[152:153], v[220:221], v[156:157]
	v_pk_fma_f32 v[234:235], v[176:177], v[92:93], v[234:235]
	v_pk_mul_f32 v[236:237], v[238:239], v[240:241]
	v_exp_f32_e32 v238, v232
	v_mul_f32_e32 v232, 0xbfb8aa3b, v231
	v_exp_f32_e32 v239, v232
	v_pk_mul_f32 v[232:233], v[234:235], v[236:237]
	v_add_f32_e32 v234, 1.0, v238
	v_rcp_f32_e32 v234, v234
	v_add_f32_e32 v235, 1.0, v239
	v_rcp_f32_e32 v235, v235
	v_pk_fma_f32 v[218:219], v[148:149], v[218:219], v[220:221]
	v_pk_fma_f32 v[228:229], v[130:131], v[228:229], v[142:143]
	v_pk_fma_f32 v[218:219], v[188:189], v[144:145], v[218:219]
	v_pk_fma_f32 v[226:227], v[134:135], v[226:227], v[228:229]
	v_mul_f32_e32 v220, 0xbfb8aa3b, v218
	v_pk_mul_f32 v[228:229], v[230:231], v[234:235]
	v_exp_f32_e32 v230, v220
	v_mul_f32_e32 v220, 0xbfb8aa3b, v219
	v_exp_f32_e32 v231, v220
	v_pk_fma_f32 v[226:227], v[186:187], v[138:139], v[226:227]
	v_pk_fma_f32 v[216:217], v[128:129], v[216:217], v[140:141]
	v_pk_mul_f32 v[220:221], v[226:227], v[228:229]
	v_add_f32_e32 v226, 1.0, v230
	v_add_f32_e32 v227, 1.0, v231
	v_rcp_f32_e32 v226, v226
	v_rcp_f32_e32 v227, v227
	v_pk_fma_f32 v[214:215], v[132:133], v[214:215], v[216:217]
	v_pk_fma_f32 v[212:213], v[86:87], v[212:213], v[98:99]
	v_pk_fma_f32 v[214:215], v[184:185], v[136:137], v[214:215]
	v_pk_mul_f32 v[216:217], v[218:219], v[226:227]
	v_pk_fma_f32 v[218:219], v[102:103], v[224:225], v[114:115]
	v_pk_mul_f32 v[214:215], v[214:215], v[216:217]
	v_pk_fma_f32 v[218:219], v[110:111], v[222:223], v[218:219]
	v_pk_fma_f32 v[210:211], v[90:91], v[210:211], v[212:213]
	v_pk_fma_f32 v[218:219], v[182:183], v[106:107], v[218:219]
	v_pk_fma_f32 v[210:211], v[178:179], v[94:95], v[210:211]
	v_mul_f32_e32 v222, 0xbfb8aa3b, v218
	v_mul_f32_e32 v223, 0xbfb8aa3b, v219
	v_exp_f32_e32 v222, v222
	v_exp_f32_e32 v223, v223
	v_add_f32_e32 v216, 1.0, v222
	v_add_f32_e32 v217, 1.0, v223
	v_rcp_f32_e32 v216, v216
	v_rcp_f32_e32 v217, v217
	s_nop 0
	v_pk_mul_f32 v[212:213], v[218:219], v[216:217]
	s_nop 0
	v_pk_mul_f32 v[216:217], v[210:211], v[212:213]
	v_cvt_pk_bf16_f32 v210, v214, v215
	v_mov_b64_e32 v[214:215], s[20:21]
	v_mad_i64_i32 v[214:215], s[10:11], v246, s83, v[214:215]
	v_cvt_pk_bf16_f32 v211, v220, v221
	v_cvt_pk_bf16_f32 v212, v232, v233
	v_cvt_pk_bf16_f32 v213, v216, v217
	v_lshl_add_u64 v[214:215], v[208:209], 1, v[214:215]
	global_store_dwordx4 v[214:215], v[210:213], off
.LBB0_1468:
	s_andn2_saveexec_b64 s[8:9], s[8:9]
	s_or_b64 exec, exec, s[8:9]
	v_mov_b32_dpp v210, v188 row_ror:1 row_mask:0xf bank_mask:0xf bound_ctrl:1
	v_mov_b32_dpp v188, v188 row_ror:2 row_mask:0xf bank_mask:0xf bound_ctrl:1
	v_mov_b32_dpp v211, v189 row_ror:1 row_mask:0xf bank_mask:0xf bound_ctrl:1
	v_mov_b32_dpp v189, v189 row_ror:2 row_mask:0xf bank_mask:0xf bound_ctrl:1
	v_mov_b32_dpp v188, v172 row_shr:2 row_mask:0xf bank_mask:0xf
	v_mov_b32_dpp v210, v172 row_shr:1 row_mask:0xf bank_mask:0xf
	v_mov_b32_dpp v189, v173 row_shr:2 row_mask:0xf bank_mask:0xf
	v_mov_b32_dpp v211, v173 row_shr:1 row_mask:0xf bank_mask:0xf
	v_pk_fma_f32 v[188:189], v[152:153], v[188:189], v[156:157]
	v_mov_b32_dpp v212, v184 row_ror:1 row_mask:0xf bank_mask:0xf bound_ctrl:1
	v_pk_fma_f32 v[188:189], v[148:149], v[210:211], v[188:189]
	v_mov_b32_dpp v184, v184 row_ror:2 row_mask:0xf bank_mask:0xf bound_ctrl:1
	v_pk_fma_f32 v[188:189], v[172:173], v[144:145], v[188:189]
	v_mov_b32_dpp v213, v185 row_ror:1 row_mask:0xf bank_mask:0xf bound_ctrl:1
	v_mul_f32_e32 v210, 0xbfb8aa3b, v188
	v_mul_f32_e32 v211, 0xbfb8aa3b, v189
	v_exp_f32_e32 v210, v210
	v_exp_f32_e32 v211, v211
	v_mov_b32_dpp v185, v185 row_ror:2 row_mask:0xf bank_mask:0xf bound_ctrl:1
	v_mov_b32_dpp v184, v168 row_shr:2 row_mask:0xf bank_mask:0xf
	v_add_f32_e32 v210, 1.0, v210
	v_add_f32_e32 v211, 1.0, v211
	v_rcp_f32_e32 v210, v210
	v_rcp_f32_e32 v211, v211
	v_mov_b32_dpp v185, v169 row_shr:2 row_mask:0xf bank_mask:0xf
	v_mov_b32_dpp v212, v168 row_shr:1 row_mask:0xf bank_mask:0xf
	v_mov_b32_dpp v213, v169 row_shr:1 row_mask:0xf bank_mask:0xf
	v_pk_fma_f32 v[184:185], v[128:129], v[184:185], v[140:141]
	v_pk_mul_f32 v[188:189], v[188:189], v[210:211]
	v_pk_fma_f32 v[184:185], v[132:133], v[212:213], v[184:185]
	v_mov_b32_dpp v210, v186 row_ror:1 row_mask:0xf bank_mask:0xf bound_ctrl:1
	v_pk_fma_f32 v[184:185], v[168:169], v[136:137], v[184:185]
	v_mov_b32_dpp v186, v186 row_ror:2 row_mask:0xf bank_mask:0xf bound_ctrl:1
	v_pk_mul_f32 v[184:185], v[184:185], v[188:189]
	v_mov_b32_dpp v188, v190 row_ror:1 row_mask:0xf bank_mask:0xf bound_ctrl:1
	v_mov_b32_dpp v190, v190 row_ror:2 row_mask:0xf bank_mask:0xf bound_ctrl:1
	v_mov_b32_dpp v189, v191 row_ror:1 row_mask:0xf bank_mask:0xf bound_ctrl:1
	v_mov_b32_dpp v191, v191 row_ror:2 row_mask:0xf bank_mask:0xf bound_ctrl:1
	v_mov_b32_dpp v190, v174 row_shr:2 row_mask:0xf bank_mask:0xf
	v_mov_b32_dpp v188, v174 row_shr:1 row_mask:0xf bank_mask:0xf
; __device__ __forceinline__ unsigned pk2(float lo, float hi) { const f32x2 v = {lo, hi}; return __builtin_bit_cast(unsigned, __builtin_convertvector(v, bf16x2_t)); }
; __device__ __forceinline__ float silu(float x) { return x * __builtin_amdgcn_rcpf(1.f + __builtin_amdgcn_exp2f(-1.4426950408889634f * x)); }
;     __device__ __forceinline__ void operator()(f32x4 (&acc)[2][2][4][2], const Unit& u, int, int, int, int) const {
;     ...
;         for (int ai = 0; ai < 2; ++ai)
; #pragma unroll
;             for (int m = 0; m < 4; ++m) { float r[8];
; #pragma unroll
;                 for (int n = 0; n < 2; ++n)
; #pragma unroll
;                     for (int e = 0; e < 4; ++e) { const float A = acc[ai][0][m][n][e], Gv = acc[ai][1][m][n][e];
;                         const float Ap = m > 0 ? acc[ai][0][m > 0 ? m - 1 : 0][n][e] : 0.f, Gp = m > 0 ? acc[ai][1][m > 0 ? m - 1 : 0][n][e] : 0.f;
;                         const float a1 = dpp_prev(A, Ap, 1), a2 = dpp_prev(A, Ap, 2), g1 = dpp_prev(Gv, Gp, 1), g2 = dpp_prev(Gv, Gp, 2);
;                         const float ca = ba[n][e] + wa0[n][e] * a2 + wa1[n][e] * a1 + wa2[n][e] * A, cg = bg[n][e] + wg0[n][e] * g2 + wg1[n][e] * g1 + wg2[n][e] * Gv;
;                         r[4 * n + e] = silu(ca) * cg; }
;                 if (!(m == 0 && fr < 2)) { u32x4 w; w.x = pk2(r[0], r[1]); w.y = pk2(r[2], r[3]); w.z = pk2(r[4], r[5]); w.w = pk2(r[6], r[7]);
;                     *(u32x4*)(ACT + (size_t)(rowt + ai * HALF + m * 16) * NFF + f0) = w; }
	v_mov_b32_dpp v191, v175 row_shr:2 row_mask:0xf bank_mask:0xf
	v_mov_b32_dpp v189, v175 row_shr:1 row_mask:0xf bank_mask:0xf
	v_pk_fma_f32 v[190:191], v[154:155], v[190:191], v[158:159]
	v_mov_b32_dpp v211, v187 row_ror:1 row_mask:0xf bank_mask:0xf bound_ctrl:1
	v_pk_fma_f32 v[188:189], v[150:151], v[188:189], v[190:191]
	v_mov_b32_dpp v187, v187 row_ror:2 row_mask:0xf bank_mask:0xf bound_ctrl:1
	v_pk_fma_f32 v[188:189], v[174:175], v[146:147], v[188:189]
	v_mov_b32_dpp v186, v170 row_shr:2 row_mask:0xf bank_mask:0xf
	v_mul_f32_e32 v190, 0xbfb8aa3b, v188
	v_mul_f32_e32 v191, 0xbfb8aa3b, v189
	v_exp_f32_e32 v190, v190
	v_exp_f32_e32 v191, v191
	v_mov_b32_dpp v187, v171 row_shr:2 row_mask:0xf bank_mask:0xf
	v_mov_b32_dpp v210, v170 row_shr:1 row_mask:0xf bank_mask:0xf
	v_add_f32_e32 v190, 1.0, v190
	v_add_f32_e32 v191, 1.0, v191
	v_rcp_f32_e32 v190, v190
	v_rcp_f32_e32 v191, v191
	v_mov_b32_dpp v211, v171 row_shr:1 row_mask:0xf bank_mask:0xf
	v_pk_fma_f32 v[186:187], v[130:131], v[186:187], v[142:143]
	v_pk_mul_f32 v[188:189], v[188:189], v[190:191]
	v_pk_fma_f32 v[186:187], v[134:135], v[210:211], v[186:187]
	v_mov_b32_dpp v190, v176 row_ror:1 row_mask:0xf bank_mask:0xf bound_ctrl:1
	v_pk_fma_f32 v[186:187], v[170:171], v[138:139], v[186:187]
	v_mov_b32_dpp v176, v176 row_ror:2 row_mask:0xf bank_mask:0xf bound_ctrl:1
	v_pk_mul_f32 v[186:187], v[186:187], v[188:189]
	v_mov_b32_dpp v188, v180 row_ror:1 row_mask:0xf bank_mask:0xf bound_ctrl:1
	v_mov_b32_dpp v180, v180 row_ror:2 row_mask:0xf bank_mask:0xf bound_ctrl:1
	v_mov_b32_dpp v189, v181 row_ror:1 row_mask:0xf bank_mask:0xf bound_ctrl:1
	v_mov_b32_dpp v181, v181 row_ror:2 row_mask:0xf bank_mask:0xf bound_ctrl:1
	v_mov_b32_dpp v180, v164 row_shr:2 row_mask:0xf bank_mask:0xf
	v_mov_b32_dpp v188, v164 row_shr:1 row_mask:0xf bank_mask:0xf
	v_mov_b32_dpp v181, v165 row_shr:2 row_mask:0xf bank_mask:0xf
	v_mov_b32_dpp v189, v165 row_shr:1 row_mask:0xf bank_mask:0xf
	v_pk_fma_f32 v[180:181], v[100:101], v[180:181], v[112:113]
	v_mov_b32_dpp v191, v177 row_ror:1 row_mask:0xf bank_mask:0xf bound_ctrl:1
	v_pk_fma_f32 v[180:181], v[108:109], v[188:189], v[180:181]
	v_mov_b32_dpp v177, v177 row_ror:2 row_mask:0xf bank_mask:0xf bound_ctrl:1
	v_pk_fma_f32 v[180:181], v[164:165], v[104:105], v[180:181]
	v_mov_b32_dpp v176, v160 row_shr:2 row_mask:0xf bank_mask:0xf
	v_mul_f32_e32 v188, 0xbfb8aa3b, v180
	v_mul_f32_e32 v189, 0xbfb8aa3b, v181
	v_exp_f32_e32 v188, v188
	v_exp_f32_e32 v189, v189
	v_mov_b32_dpp v177, v161 row_shr:2 row_mask:0xf bank_mask:0xf
	v_mov_b32_dpp v190, v160 row_shr:1 row_mask:0xf bank_mask:0xf
	v_add_f32_e32 v188, 1.0, v188
	v_add_f32_e32 v189, 1.0, v189
	v_rcp_f32_e32 v188, v188
	v_rcp_f32_e32 v189, v189
	v_mov_b32_dpp v191, v161 row_shr:1 row_mask:0xf bank_mask:0xf
	v_pk_fma_f32 v[176:177], v[84:85], v[176:177], v[96:97]
	v_pk_mul_f32 v[180:181], v[180:181], v[188:189]
	v_pk_fma_f32 v[176:177], v[88:89], v[190:191], v[176:177]
	v_mov_b32_dpp v188, v178 row_ror:1 row_mask:0xf bank_mask:0xf bound_ctrl:1
	v_pk_fma_f32 v[176:177], v[160:161], v[92:93], v[176:177]
	v_mov_b32_dpp v178, v178 row_ror:2 row_mask:0xf bank_mask:0xf bound_ctrl:1
	v_pk_mul_f32 v[176:177], v[176:177], v[180:181]
	v_mov_b32_dpp v180, v182 row_ror:1 row_mask:0xf bank_mask:0xf bound_ctrl:1
	v_mov_b32_dpp v182, v182 row_ror:2 row_mask:0xf bank_mask:0xf bound_ctrl:1
	v_mov_b32_dpp v181, v183 row_ror:1 row_mask:0xf bank_mask:0xf bound_ctrl:1
	v_mov_b32_dpp v183, v183 row_ror:2 row_mask:0xf bank_mask:0xf bound_ctrl:1
	v_mov_b32_dpp v182, v166 row_shr:2 row_mask:0xf bank_mask:0xf
	v_mov_b32_dpp v180, v166 row_shr:1 row_mask:0xf bank_mask:0xf
	v_mov_b32_dpp v183, v167 row_shr:2 row_mask:0xf bank_mask:0xf
	v_mov_b32_dpp v181, v167 row_shr:1 row_mask:0xf bank_mask:0xf
	v_pk_fma_f32 v[182:183], v[102:103], v[182:183], v[114:115]
	v_mov_b32_dpp v189, v179 row_ror:1 row_mask:0xf bank_mask:0xf bound_ctrl:1
	v_pk_fma_f32 v[180:181], v[110:111], v[180:181], v[182:183]
	v_mov_b32_dpp v179, v179 row_ror:2 row_mask:0xf bank_mask:0xf bound_ctrl:1
	v_pk_fma_f32 v[180:181], v[166:167], v[106:107], v[180:181]
	v_mov_b32_dpp v178, v162 row_shr:2 row_mask:0xf bank_mask:0xf
	v_mul_f32_e32 v182, 0xbfb8aa3b, v180
	v_mul_f32_e32 v183, 0xbfb8aa3b, v181
	v_exp_f32_e32 v182, v182
	v_exp_f32_e32 v183, v183
	v_mov_b32_dpp v179, v163 row_shr:2 row_mask:0xf bank_mask:0xf
	v_mov_b32_dpp v188, v162 row_shr:1 row_mask:0xf bank_mask:0xf
	v_add_f32_e32 v182, 1.0, v182
	v_add_f32_e32 v183, 1.0, v183
	v_rcp_f32_e32 v182, v182
	v_rcp_f32_e32 v183, v183
	v_mov_b32_dpp v189, v163 row_shr:1 row_mask:0xf bank_mask:0xf
	v_pk_fma_f32 v[178:179], v[86:87], v[178:179], v[98:99]
	v_pk_mul_f32 v[180:181], v[180:181], v[182:183]
	v_pk_fma_f32 v[178:179], v[90:91], v[188:189], v[178:179]
	v_cvt_pk_bf16_f32 v182, v176, v177
	v_pk_fma_f32 v[178:179], v[162:163], v[94:95], v[178:179]
	v_or_b32_e32 v176, 16, v246
	v_pk_mul_f32 v[178:179], v[178:179], v[180:181]
	v_cvt_pk_bf16_f32 v180, v184, v185
	v_cvt_pk_bf16_f32 v183, v178, v179
	v_mov_b64_e32 v[178:179], s[20:21]
	v_mad_i64_i32 v[184:185], s[8:9], v176, s83, v[178:179]
	v_lshlrev_b64 v[176:177], 1, v[208:209]
	v_cvt_pk_bf16_f32 v181, v186, v187
	v_lshl_add_u64 v[184:185], v[184:185], 0, v[176:177]
	global_store_dwordx4 v[184:185], v[180:183], off
	s_nop 1
	v_mov_b32_dpp v180, v172 row_ror:1 row_mask:0xf bank_mask:0xf bound_ctrl:1
	v_mov_b32_dpp v172, v172 row_ror:2 row_mask:0xf bank_mask:0xf bound_ctrl:1
	v_mov_b32_dpp v181, v173 row_ror:1 row_mask:0xf bank_mask:0xf bound_ctrl:1
	v_mov_b32_dpp v173, v173 row_ror:2 row_mask:0xf bank_mask:0xf bound_ctrl:1
	v_mov_b32_dpp v172, v124 row_shr:2 row_mask:0xf bank_mask:0xf
; __device__ __forceinline__ unsigned pk2(float lo, float hi) { const f32x2 v = {lo, hi}; return __builtin_bit_cast(unsigned, __builtin_convertvector(v, bf16x2_t)); }
; __device__ __forceinline__ float silu(float x) { return x * __builtin_amdgcn_rcpf(1.f + __builtin_amdgcn_exp2f(-1.4426950408889634f * x)); }
;     __device__ __forceinline__ void operator()(f32x4 (&acc)[2][2][4][2], const Unit& u, int, int, int, int) const {
;     ...
;         for (int ai = 0; ai < 2; ++ai)
; #pragma unroll
;             for (int m = 0; m < 4; ++m) { float r[8];
; #pragma unroll
;                 for (int n = 0; n < 2; ++n)
; #pragma unroll
;                     for (int e = 0; e < 4; ++e) { const float A = acc[ai][0][m][n][e], Gv = acc[ai][1][m][n][e];
;                         const float Ap = m > 0 ? acc[ai][0][m > 0 ? m - 1 : 0][n][e] : 0.f, Gp = m > 0 ? acc[ai][1][m > 0 ? m - 1 : 0][n][e] : 0.f;
;                         const float a1 = dpp_prev(A, Ap, 1), a2 = dpp_prev(A, Ap, 2), g1 = dpp_prev(Gv, Gp, 1), g2 = dpp_prev(Gv, Gp, 2);
;                         const float ca = ba[n][e] + wa0[n][e] * a2 + wa1[n][e] * a1 + wa2[n][e] * A, cg = bg[n][e] + wg0[n][e] * g2 + wg1[n][e] * g1 + wg2[n][e] * Gv;
;                         r[4 * n + e] = silu(ca) * cg; }
;                 if (!(m == 0 && fr < 2)) { u32x4 w; w.x = pk2(r[0], r[1]); w.y = pk2(r[2], r[3]); w.z = pk2(r[4], r[5]); w.w = pk2(r[6], r[7]);
;                     *(u32x4*)(ACT + (size_t)(rowt + ai * HALF + m * 16) * NFF + f0) = w; }
	v_mov_b32_dpp v180, v124 row_shr:1 row_mask:0xf bank_mask:0xf
	v_mov_b32_dpp v173, v125 row_shr:2 row_mask:0xf bank_mask:0xf
	v_mov_b32_dpp v181, v125 row_shr:1 row_mask:0xf bank_mask:0xf
	v_pk_fma_f32 v[172:173], v[152:153], v[172:173], v[156:157]
	v_mov_b32_dpp v182, v168 row_ror:1 row_mask:0xf bank_mask:0xf bound_ctrl:1
	v_pk_fma_f32 v[172:173], v[148:149], v[180:181], v[172:173]
	v_mov_b32_dpp v168, v168 row_ror:2 row_mask:0xf bank_mask:0xf bound_ctrl:1
	v_pk_fma_f32 v[172:173], v[124:125], v[144:145], v[172:173]
	v_mov_b32_dpp v183, v169 row_ror:1 row_mask:0xf bank_mask:0xf bound_ctrl:1
	v_mul_f32_e32 v180, 0xbfb8aa3b, v172
	v_mul_f32_e32 v181, 0xbfb8aa3b, v173
	v_exp_f32_e32 v180, v180
	v_exp_f32_e32 v181, v181
	v_mov_b32_dpp v169, v169 row_ror:2 row_mask:0xf bank_mask:0xf bound_ctrl:1
	v_mov_b32_dpp v168, v116 row_shr:2 row_mask:0xf bank_mask:0xf
	v_add_f32_e32 v180, 1.0, v180
	v_add_f32_e32 v181, 1.0, v181
	v_rcp_f32_e32 v180, v180
	v_rcp_f32_e32 v181, v181
	v_mov_b32_dpp v169, v117 row_shr:2 row_mask:0xf bank_mask:0xf
	v_mov_b32_dpp v182, v116 row_shr:1 row_mask:0xf bank_mask:0xf
	v_mov_b32_dpp v183, v117 row_shr:1 row_mask:0xf bank_mask:0xf
	v_pk_fma_f32 v[168:169], v[128:129], v[168:169], v[140:141]
	v_pk_mul_f32 v[172:173], v[172:173], v[180:181]
	v_pk_fma_f32 v[168:169], v[132:133], v[182:183], v[168:169]
	v_mov_b32_dpp v180, v170 row_ror:1 row_mask:0xf bank_mask:0xf bound_ctrl:1
	v_pk_fma_f32 v[168:169], v[116:117], v[136:137], v[168:169]
	v_mov_b32_dpp v170, v170 row_ror:2 row_mask:0xf bank_mask:0xf bound_ctrl:1
	v_pk_mul_f32 v[168:169], v[168:169], v[172:173]
	v_mov_b32_dpp v172, v174 row_ror:1 row_mask:0xf bank_mask:0xf bound_ctrl:1
	v_mov_b32_dpp v174, v174 row_ror:2 row_mask:0xf bank_mask:0xf bound_ctrl:1
	v_mov_b32_dpp v173, v175 row_ror:1 row_mask:0xf bank_mask:0xf bound_ctrl:1
	v_mov_b32_dpp v175, v175 row_ror:2 row_mask:0xf bank_mask:0xf bound_ctrl:1
	v_mov_b32_dpp v174, v126 row_shr:2 row_mask:0xf bank_mask:0xf
	v_mov_b32_dpp v172, v126 row_shr:1 row_mask:0xf bank_mask:0xf
	v_mov_b32_dpp v175, v127 row_shr:2 row_mask:0xf bank_mask:0xf
	v_mov_b32_dpp v173, v127 row_shr:1 row_mask:0xf bank_mask:0xf
	v_pk_fma_f32 v[174:175], v[154:155], v[174:175], v[158:159]
	v_mov_b32_dpp v181, v171 row_ror:1 row_mask:0xf bank_mask:0xf bound_ctrl:1
	v_pk_fma_f32 v[172:173], v[150:151], v[172:173], v[174:175]
	v_mov_b32_dpp v171, v171 row_ror:2 row_mask:0xf bank_mask:0xf bound_ctrl:1
	v_pk_fma_f32 v[172:173], v[126:127], v[146:147], v[172:173]
	v_mov_b32_dpp v170, v118 row_shr:2 row_mask:0xf bank_mask:0xf
	v_mul_f32_e32 v174, 0xbfb8aa3b, v172
	v_mul_f32_e32 v175, 0xbfb8aa3b, v173
	v_exp_f32_e32 v174, v174
	v_exp_f32_e32 v175, v175
	v_mov_b32_dpp v171, v119 row_shr:2 row_mask:0xf bank_mask:0xf
	v_mov_b32_dpp v180, v118 row_shr:1 row_mask:0xf bank_mask:0xf
	v_add_f32_e32 v174, 1.0, v174
	v_add_f32_e32 v175, 1.0, v175
	v_rcp_f32_e32 v174, v174
	v_rcp_f32_e32 v175, v175
	v_mov_b32_dpp v181, v119 row_shr:1 row_mask:0xf bank_mask:0xf
	v_pk_fma_f32 v[170:171], v[130:131], v[170:171], v[142:143]
	v_pk_mul_f32 v[172:173], v[172:173], v[174:175]
	v_pk_fma_f32 v[170:171], v[134:135], v[180:181], v[170:171]
	v_mov_b32_dpp v174, v160 row_ror:1 row_mask:0xf bank_mask:0xf bound_ctrl:1
	v_pk_fma_f32 v[170:171], v[118:119], v[138:139], v[170:171]
	v_mov_b32_dpp v160, v160 row_ror:2 row_mask:0xf bank_mask:0xf bound_ctrl:1
	v_pk_mul_f32 v[170:171], v[170:171], v[172:173]
	v_mov_b32_dpp v172, v164 row_ror:1 row_mask:0xf bank_mask:0xf bound_ctrl:1
	v_mov_b32_dpp v164, v164 row_ror:2 row_mask:0xf bank_mask:0xf bound_ctrl:1
	v_mov_b32_dpp v173, v165 row_ror:1 row_mask:0xf bank_mask:0xf bound_ctrl:1
	v_mov_b32_dpp v165, v165 row_ror:2 row_mask:0xf bank_mask:0xf bound_ctrl:1
	v_mov_b32_dpp v164, v76 row_shr:2 row_mask:0xf bank_mask:0xf
	v_mov_b32_dpp v172, v76 row_shr:1 row_mask:0xf bank_mask:0xf
	v_mov_b32_dpp v165, v77 row_shr:2 row_mask:0xf bank_mask:0xf
	v_mov_b32_dpp v173, v77 row_shr:1 row_mask:0xf bank_mask:0xf
	v_pk_fma_f32 v[164:165], v[100:101], v[164:165], v[112:113]
	v_mov_b32_dpp v175, v161 row_ror:1 row_mask:0xf bank_mask:0xf bound_ctrl:1
	v_pk_fma_f32 v[164:165], v[108:109], v[172:173], v[164:165]
	v_mov_b32_dpp v161, v161 row_ror:2 row_mask:0xf bank_mask:0xf bound_ctrl:1
	v_pk_fma_f32 v[164:165], v[76:77], v[104:105], v[164:165]
	v_mov_b32_dpp v160, v68 row_shr:2 row_mask:0xf bank_mask:0xf
	v_mul_f32_e32 v172, 0xbfb8aa3b, v164
	v_mul_f32_e32 v173, 0xbfb8aa3b, v165
	v_exp_f32_e32 v172, v172
	v_exp_f32_e32 v173, v173
	v_mov_b32_dpp v161, v69 row_shr:2 row_mask:0xf bank_mask:0xf
	v_mov_b32_dpp v174, v68 row_shr:1 row_mask:0xf bank_mask:0xf
	v_add_f32_e32 v172, 1.0, v172
	v_add_f32_e32 v173, 1.0, v173
	v_rcp_f32_e32 v172, v172
	v_rcp_f32_e32 v173, v173
	v_mov_b32_dpp v175, v69 row_shr:1 row_mask:0xf bank_mask:0xf
	v_pk_fma_f32 v[160:161], v[84:85], v[160:161], v[96:97]
	v_pk_mul_f32 v[164:165], v[164:165], v[172:173]
	v_pk_fma_f32 v[160:161], v[88:89], v[174:175], v[160:161]
	v_mov_b32_dpp v172, v162 row_ror:1 row_mask:0xf bank_mask:0xf bound_ctrl:1
	v_pk_fma_f32 v[160:161], v[68:69], v[92:93], v[160:161]
	v_mov_b32_dpp v162, v162 row_ror:2 row_mask:0xf bank_mask:0xf bound_ctrl:1
	v_pk_mul_f32 v[164:165], v[160:161], v[164:165]
	v_mov_b32_dpp v160, v166 row_ror:1 row_mask:0xf bank_mask:0xf bound_ctrl:1
	v_mov_b32_dpp v166, v166 row_ror:2 row_mask:0xf bank_mask:0xf bound_ctrl:1
	v_mov_b32_dpp v161, v167 row_ror:1 row_mask:0xf bank_mask:0xf bound_ctrl:1
	v_mov_b32_dpp v167, v167 row_ror:2 row_mask:0xf bank_mask:0xf bound_ctrl:1
	v_mov_b32_dpp v166, v78 row_shr:2 row_mask:0xf bank_mask:0xf
	v_mov_b32_dpp v160, v78 row_shr:1 row_mask:0xf bank_mask:0xf
; __device__ __forceinline__ unsigned pk2(float lo, float hi) { const f32x2 v = {lo, hi}; return __builtin_bit_cast(unsigned, __builtin_convertvector(v, bf16x2_t)); }
; __device__ __forceinline__ float silu(float x) { return x * __builtin_amdgcn_rcpf(1.f + __builtin_amdgcn_exp2f(-1.4426950408889634f * x)); }
;     __device__ __forceinline__ void operator()(f32x4 (&acc)[2][2][4][2], const Unit& u, int, int, int, int) const {
;     ...
;         for (int ai = 0; ai < 2; ++ai)
; #pragma unroll
;             for (int m = 0; m < 4; ++m) { float r[8];
; #pragma unroll
;                 for (int n = 0; n < 2; ++n)
; #pragma unroll
;                     for (int e = 0; e < 4; ++e) { const float A = acc[ai][0][m][n][e], Gv = acc[ai][1][m][n][e];
;                         const float Ap = m > 0 ? acc[ai][0][m > 0 ? m - 1 : 0][n][e] : 0.f, Gp = m > 0 ? acc[ai][1][m > 0 ? m - 1 : 0][n][e] : 0.f;
;                         const float a1 = dpp_prev(A, Ap, 1), a2 = dpp_prev(A, Ap, 2), g1 = dpp_prev(Gv, Gp, 1), g2 = dpp_prev(Gv, Gp, 2);
;                         const float ca = ba[n][e] + wa0[n][e] * a2 + wa1[n][e] * a1 + wa2[n][e] * A, cg = bg[n][e] + wg0[n][e] * g2 + wg1[n][e] * g1 + wg2[n][e] * Gv;
;                         r[4 * n + e] = silu(ca) * cg; }
;                 if (!(m == 0 && fr < 2)) { u32x4 w; w.x = pk2(r[0], r[1]); w.y = pk2(r[2], r[3]); w.z = pk2(r[4], r[5]); w.w = pk2(r[6], r[7]);
;                     *(u32x4*)(ACT + (size_t)(rowt + ai * HALF + m * 16) * NFF + f0) = w; }
	v_mov_b32_dpp v167, v79 row_shr:2 row_mask:0xf bank_mask:0xf
	v_mov_b32_dpp v161, v79 row_shr:1 row_mask:0xf bank_mask:0xf
	v_pk_fma_f32 v[166:167], v[102:103], v[166:167], v[114:115]
	v_mov_b32_dpp v173, v163 row_ror:1 row_mask:0xf bank_mask:0xf bound_ctrl:1
	v_pk_fma_f32 v[160:161], v[110:111], v[160:161], v[166:167]
	v_mov_b32_dpp v163, v163 row_ror:2 row_mask:0xf bank_mask:0xf bound_ctrl:1
	v_pk_fma_f32 v[160:161], v[78:79], v[106:107], v[160:161]
	v_mov_b32_dpp v162, v70 row_shr:2 row_mask:0xf bank_mask:0xf
	v_mul_f32_e32 v166, 0xbfb8aa3b, v160
	v_mul_f32_e32 v167, 0xbfb8aa3b, v161
	v_exp_f32_e32 v166, v166
	v_exp_f32_e32 v167, v167
	v_mov_b32_dpp v163, v71 row_shr:2 row_mask:0xf bank_mask:0xf
	v_mov_b32_dpp v172, v70 row_shr:1 row_mask:0xf bank_mask:0xf
	v_add_f32_e32 v166, 1.0, v166
	v_add_f32_e32 v167, 1.0, v167
	v_rcp_f32_e32 v166, v166
	v_rcp_f32_e32 v167, v167
	v_mov_b32_dpp v173, v71 row_shr:1 row_mask:0xf bank_mask:0xf
	v_pk_fma_f32 v[162:163], v[86:87], v[162:163], v[98:99]
	v_pk_mul_f32 v[160:161], v[160:161], v[166:167]
	v_pk_fma_f32 v[162:163], v[90:91], v[172:173], v[162:163]
	s_nop 0
	v_pk_fma_f32 v[162:163], v[70:71], v[94:95], v[162:163]
	s_nop 0
	v_pk_mul_f32 v[166:167], v[162:163], v[160:161]
	v_cvt_pk_bf16_f32 v162, v164, v165
	v_or_b32_e32 v164, 32, v246
	v_mad_i64_i32 v[164:165], s[8:9], v164, s83, v[178:179]
	v_cvt_pk_bf16_f32 v160, v168, v169
	v_cvt_pk_bf16_f32 v161, v170, v171
	v_cvt_pk_bf16_f32 v163, v166, v167
	v_lshl_add_u64 v[164:165], v[164:165], 0, v[176:177]
	global_store_dwordx4 v[164:165], v[160:163], off
	s_nop 1
	v_mov_b32_dpp v160, v124 row_ror:1 row_mask:0xf bank_mask:0xf bound_ctrl:1
	v_mov_b32_dpp v124, v124 row_ror:2 row_mask:0xf bank_mask:0xf bound_ctrl:1
	v_mov_b32_dpp v161, v125 row_ror:1 row_mask:0xf bank_mask:0xf bound_ctrl:1
	v_mov_b32_dpp v125, v125 row_ror:2 row_mask:0xf bank_mask:0xf bound_ctrl:1
	v_mov_b32_dpp v124, v120 row_shr:2 row_mask:0xf bank_mask:0xf
	v_mov_b32_dpp v160, v120 row_shr:1 row_mask:0xf bank_mask:0xf
	v_mov_b32_dpp v125, v121 row_shr:2 row_mask:0xf bank_mask:0xf
	v_mov_b32_dpp v161, v121 row_shr:1 row_mask:0xf bank_mask:0xf
	v_pk_fma_f32 v[124:125], v[152:153], v[124:125], v[156:157]
	v_mov_b32_dpp v162, v116 row_ror:1 row_mask:0xf bank_mask:0xf bound_ctrl:1
	v_pk_fma_f32 v[124:125], v[148:149], v[160:161], v[124:125]
	v_mov_b32_dpp v116, v116 row_ror:2 row_mask:0xf bank_mask:0xf bound_ctrl:1
	v_pk_fma_f32 v[120:121], v[120:121], v[144:145], v[124:125]
	v_mov_b32_dpp v163, v117 row_ror:1 row_mask:0xf bank_mask:0xf bound_ctrl:1
	v_mul_f32_e32 v124, 0xbfb8aa3b, v120
	v_mul_f32_e32 v125, 0xbfb8aa3b, v121
	v_exp_f32_e32 v124, v124
	v_exp_f32_e32 v125, v125
	v_mov_b32_dpp v117, v117 row_ror:2 row_mask:0xf bank_mask:0xf bound_ctrl:1
	v_mov_b32_dpp v116, v80 row_shr:2 row_mask:0xf bank_mask:0xf
	v_add_f32_e32 v124, 1.0, v124
	v_add_f32_e32 v125, 1.0, v125
	v_rcp_f32_e32 v124, v124
	v_rcp_f32_e32 v125, v125
	v_mov_b32_dpp v117, v81 row_shr:2 row_mask:0xf bank_mask:0xf
	v_mov_b32_dpp v162, v80 row_shr:1 row_mask:0xf bank_mask:0xf
	v_mov_b32_dpp v163, v81 row_shr:1 row_mask:0xf bank_mask:0xf
	v_pk_fma_f32 v[116:117], v[128:129], v[116:117], v[140:141]
	s_nop 0
	v_pk_fma_f32 v[116:117], v[132:133], v[162:163], v[116:117]
	s_nop 0
	v_pk_fma_f32 v[80:81], v[80:81], v[136:137], v[116:117]
	v_pk_mul_f32 v[116:117], v[120:121], v[124:125]
	v_mov_b32_dpp v120, v126 row_ror:2 row_mask:0xf bank_mask:0xf bound_ctrl:1
	v_mov_b32_dpp v121, v127 row_ror:2 row_mask:0xf bank_mask:0xf bound_ctrl:1
	v_pk_mul_f32 v[80:81], v[80:81], v[116:117]
	v_mov_b32_dpp v116, v126 row_ror:1 row_mask:0xf bank_mask:0xf bound_ctrl:1
	v_mov_b32_dpp v120, v122 row_shr:2 row_mask:0xf bank_mask:0xf
	v_mov_b32_dpp v117, v127 row_ror:1 row_mask:0xf bank_mask:0xf bound_ctrl:1
	v_mov_b32_dpp v121, v123 row_shr:2 row_mask:0xf bank_mask:0xf
	v_mov_b32_dpp v116, v122 row_shr:1 row_mask:0xf bank_mask:0xf
	v_mov_b32_dpp v117, v123 row_shr:1 row_mask:0xf bank_mask:0xf
	v_pk_fma_f32 v[120:121], v[154:155], v[120:121], v[158:159]
	v_mov_b32_dpp v124, v118 row_ror:1 row_mask:0xf bank_mask:0xf bound_ctrl:1
	v_pk_fma_f32 v[116:117], v[150:151], v[116:117], v[120:121]
	v_mov_b32_dpp v118, v118 row_ror:2 row_mask:0xf bank_mask:0xf bound_ctrl:1
	v_pk_fma_f32 v[116:117], v[122:123], v[146:147], v[116:117]
	v_mov_b32_dpp v125, v119 row_ror:1 row_mask:0xf bank_mask:0xf bound_ctrl:1
	v_mul_f32_e32 v120, 0xbfb8aa3b, v116
	v_mul_f32_e32 v121, 0xbfb8aa3b, v117
	v_exp_f32_e32 v120, v120
	v_exp_f32_e32 v121, v121
	v_mov_b32_dpp v119, v119 row_ror:2 row_mask:0xf bank_mask:0xf bound_ctrl:1
	v_mov_b32_dpp v118, v82 row_shr:2 row_mask:0xf bank_mask:0xf
	v_add_f32_e32 v120, 1.0, v120
	v_add_f32_e32 v121, 1.0, v121
	v_rcp_f32_e32 v120, v120
	v_rcp_f32_e32 v121, v121
	v_mov_b32_dpp v119, v83 row_shr:2 row_mask:0xf bank_mask:0xf
	v_mov_b32_dpp v124, v82 row_shr:1 row_mask:0xf bank_mask:0xf
	v_mov_b32_dpp v125, v83 row_shr:1 row_mask:0xf bank_mask:0xf
	v_pk_fma_f32 v[118:119], v[130:131], v[118:119], v[142:143]
	v_pk_mul_f32 v[116:117], v[116:117], v[120:121]
	v_pk_fma_f32 v[118:119], v[134:135], v[124:125], v[118:119]
	s_nop 0
	v_pk_fma_f32 v[82:83], v[82:83], v[138:139], v[118:119]
	v_mov_b32_dpp v118, v68 row_ror:1 row_mask:0xf bank_mask:0xf bound_ctrl:1
	v_pk_mul_f32 v[82:83], v[82:83], v[116:117]
	v_mov_b32_dpp v116, v76 row_ror:1 row_mask:0xf bank_mask:0xf bound_ctrl:1
	v_mov_b32_dpp v76, v76 row_ror:2 row_mask:0xf bank_mask:0xf bound_ctrl:1
	v_mov_b32_dpp v117, v77 row_ror:1 row_mask:0xf bank_mask:0xf bound_ctrl:1
	v_mov_b32_dpp v77, v77 row_ror:2 row_mask:0xf bank_mask:0xf bound_ctrl:1
	v_mov_b32_dpp v76, v72 row_shr:2 row_mask:0xf bank_mask:0xf
; __device__ __forceinline__ unsigned pk2(float lo, float hi) { const f32x2 v = {lo, hi}; return __builtin_bit_cast(unsigned, __builtin_convertvector(v, bf16x2_t)); }
; __device__ __forceinline__ float silu(float x) { return x * __builtin_amdgcn_rcpf(1.f + __builtin_amdgcn_exp2f(-1.4426950408889634f * x)); }
;     __device__ __forceinline__ void operator()(f32x4 (&acc)[2][2][4][2], const Unit& u, int, int, int, int) const {
;     ...
;         for (int ai = 0; ai < 2; ++ai)
; #pragma unroll
;             for (int m = 0; m < 4; ++m) { float r[8];
; #pragma unroll
;                 for (int n = 0; n < 2; ++n)
; #pragma unroll
;                     for (int e = 0; e < 4; ++e) { const float A = acc[ai][0][m][n][e], Gv = acc[ai][1][m][n][e];
;                         const float Ap = m > 0 ? acc[ai][0][m > 0 ? m - 1 : 0][n][e] : 0.f, Gp = m > 0 ? acc[ai][1][m > 0 ? m - 1 : 0][n][e] : 0.f;
;                         const float a1 = dpp_prev(A, Ap, 1), a2 = dpp_prev(A, Ap, 2), g1 = dpp_prev(Gv, Gp, 1), g2 = dpp_prev(Gv, Gp, 2);
;                         const float ca = ba[n][e] + wa0[n][e] * a2 + wa1[n][e] * a1 + wa2[n][e] * A, cg = bg[n][e] + wg0[n][e] * g2 + wg1[n][e] * g1 + wg2[n][e] * Gv;
;                         r[4 * n + e] = silu(ca) * cg; }
;                 if (!(m == 0 && fr < 2)) { u32x4 w; w.x = pk2(r[0], r[1]); w.y = pk2(r[2], r[3]); w.z = pk2(r[4], r[5]); w.w = pk2(r[6], r[7]);
;                     *(u32x4*)(ACT + (size_t)(rowt + ai * HALF + m * 16) * NFF + f0) = w; }
	v_mov_b32_dpp v116, v72 row_shr:1 row_mask:0xf bank_mask:0xf
	v_mov_b32_dpp v77, v73 row_shr:2 row_mask:0xf bank_mask:0xf
	v_mov_b32_dpp v117, v73 row_shr:1 row_mask:0xf bank_mask:0xf
	v_pk_fma_f32 v[76:77], v[100:101], v[76:77], v[112:113]
	v_mov_b32_dpp v68, v68 row_ror:2 row_mask:0xf bank_mask:0xf bound_ctrl:1
	v_pk_fma_f32 v[76:77], v[108:109], v[116:117], v[76:77]
	v_mov_b32_dpp v119, v69 row_ror:1 row_mask:0xf bank_mask:0xf bound_ctrl:1
	v_pk_fma_f32 v[72:73], v[72:73], v[104:105], v[76:77]
	v_mov_b32_dpp v69, v69 row_ror:2 row_mask:0xf bank_mask:0xf bound_ctrl:1
	v_mul_f32_e32 v76, 0xbfb8aa3b, v72
	v_mul_f32_e32 v77, 0xbfb8aa3b, v73
	v_exp_f32_e32 v76, v76
	v_exp_f32_e32 v77, v77
	v_mov_b32_dpp v68, v64 row_shr:2 row_mask:0xf bank_mask:0xf
	v_mov_b32_dpp v69, v65 row_shr:2 row_mask:0xf bank_mask:0xf
	v_add_f32_e32 v76, 1.0, v76
	v_add_f32_e32 v77, 1.0, v77
	v_rcp_f32_e32 v76, v76
	v_rcp_f32_e32 v77, v77
	v_mov_b32_dpp v118, v64 row_shr:1 row_mask:0xf bank_mask:0xf
	v_mov_b32_dpp v119, v65 row_shr:1 row_mask:0xf bank_mask:0xf
	v_pk_fma_f32 v[68:69], v[84:85], v[68:69], v[96:97]
	s_nop 0
	v_pk_fma_f32 v[68:69], v[88:89], v[118:119], v[68:69]
	s_nop 0
	v_pk_fma_f32 v[64:65], v[64:65], v[92:93], v[68:69]
	v_pk_mul_f32 v[68:69], v[72:73], v[76:77]
	v_mov_b32_dpp v72, v78 row_ror:2 row_mask:0xf bank_mask:0xf bound_ctrl:1
	v_mov_b32_dpp v73, v79 row_ror:2 row_mask:0xf bank_mask:0xf bound_ctrl:1
	v_pk_mul_f32 v[68:69], v[64:65], v[68:69]
	v_mov_b32_dpp v64, v78 row_ror:1 row_mask:0xf bank_mask:0xf bound_ctrl:1
	v_mov_b32_dpp v72, v74 row_shr:2 row_mask:0xf bank_mask:0xf
	v_mov_b32_dpp v65, v79 row_ror:1 row_mask:0xf bank_mask:0xf bound_ctrl:1
	v_mov_b32_dpp v73, v75 row_shr:2 row_mask:0xf bank_mask:0xf
	v_mov_b32_dpp v64, v74 row_shr:1 row_mask:0xf bank_mask:0xf
	v_mov_b32_dpp v65, v75 row_shr:1 row_mask:0xf bank_mask:0xf
	v_pk_fma_f32 v[72:73], v[102:103], v[72:73], v[114:115]
	v_mov_b32_dpp v76, v70 row_ror:1 row_mask:0xf bank_mask:0xf bound_ctrl:1
	v_pk_fma_f32 v[64:65], v[110:111], v[64:65], v[72:73]
	v_mov_b32_dpp v70, v70 row_ror:2 row_mask:0xf bank_mask:0xf bound_ctrl:1
	v_pk_fma_f32 v[64:65], v[74:75], v[106:107], v[64:65]
	v_mov_b32_dpp v77, v71 row_ror:1 row_mask:0xf bank_mask:0xf bound_ctrl:1
	v_mul_f32_e32 v72, 0xbfb8aa3b, v64
	v_mul_f32_e32 v73, 0xbfb8aa3b, v65
	v_exp_f32_e32 v72, v72
	v_exp_f32_e32 v73, v73
	v_mov_b32_dpp v71, v71 row_ror:2 row_mask:0xf bank_mask:0xf bound_ctrl:1
	v_mov_b32_dpp v70, v66 row_shr:2 row_mask:0xf bank_mask:0xf
	v_add_f32_e32 v72, 1.0, v72
	v_add_f32_e32 v73, 1.0, v73
	v_rcp_f32_e32 v72, v72
	v_rcp_f32_e32 v73, v73
	v_mov_b32_dpp v71, v67 row_shr:2 row_mask:0xf bank_mask:0xf
	v_mov_b32_dpp v76, v66 row_shr:1 row_mask:0xf bank_mask:0xf
	v_mov_b32_dpp v77, v67 row_shr:1 row_mask:0xf bank_mask:0xf
	v_pk_fma_f32 v[70:71], v[86:87], v[70:71], v[98:99]
	v_pk_mul_f32 v[64:65], v[64:65], v[72:73]
	v_pk_fma_f32 v[70:71], v[90:91], v[76:77], v[70:71]
	s_nop 0
	v_pk_fma_f32 v[66:67], v[66:67], v[94:95], v[70:71]
	s_nop 0
	v_pk_mul_f32 v[70:71], v[66:67], v[64:65]
	v_cvt_pk_bf16_f32 v66, v68, v69
	v_or_b32_e32 v68, 48, v246
	v_mad_i64_i32 v[68:69], s[8:9], v68, s83, v[178:179]
	v_cvt_pk_bf16_f32 v64, v80, v81
	v_cvt_pk_bf16_f32 v65, v82, v83
	v_cvt_pk_bf16_f32 v67, v70, v71
	v_lshl_add_u64 v[68:69], v[68:69], 0, v[176:177]
	global_store_dwordx4 v[68:69], v[64:67], off
	s_nop 1
	v_mov_b32_dpp v65, v195 row_ror:1 row_mask:0xf bank_mask:0xf bound_ctrl:1
	v_mov_b32_dpp v67, v195 row_ror:2 row_mask:0xf bank_mask:0xf bound_ctrl:1
	v_mov_b32_e32 v72, v65
	v_mov_b32_e32 v74, v67
	v_mov_b32_e32 v68, v65
	v_mov_b32_e32 v70, v67
	v_mov_b32_e32 v73, v65
	v_mov_b32_e32 v75, v67
	v_mov_b32_e32 v69, v65
	v_mov_b32_e32 v71, v67
	v_mov_b32_e32 v116, v65
	v_mov_b32_e32 v118, v67
	v_mov_b32_e32 v80, v65
	v_mov_b32_e32 v82, v67
	v_mov_b32_e32 v117, v65
	v_mov_b32_e32 v119, v67
	v_mov_b32_e32 v81, v65
	v_mov_b32_e32 v83, v67
	v_mov_b32_e32 v124, v65
	v_mov_b32_e32 v126, v67
	v_mov_b32_e32 v120, v65
	v_mov_b32_e32 v122, v67
	v_mov_b32_e32 v125, v65
	v_mov_b32_e32 v127, v67
	v_mov_b32_e32 v121, v65
	v_mov_b32_e32 v123, v67
	v_mov_b32_e32 v76, v65
	v_mov_b32_e32 v78, v67
	v_mov_b32_e32 v64, v65
	v_mov_b32_e32 v66, v67
	v_mov_b32_e32 v77, v65
	v_mov_b32_e32 v79, v67
	v_mov_b32_dpp v72, v60 row_shr:1 row_mask:0xf bank_mask:0xf
	v_mov_b32_dpp v74, v60 row_shr:2 row_mask:0xf bank_mask:0xf
	v_mov_b32_dpp v68, v56 row_shr:1 row_mask:0xf bank_mask:0xf
	v_mov_b32_dpp v70, v56 row_shr:2 row_mask:0xf bank_mask:0xf
	v_mov_b32_dpp v73, v61 row_shr:1 row_mask:0xf bank_mask:0xf
	v_mov_b32_dpp v75, v61 row_shr:2 row_mask:0xf bank_mask:0xf
	v_mov_b32_dpp v69, v57 row_shr:1 row_mask:0xf bank_mask:0xf
	v_mov_b32_dpp v71, v57 row_shr:2 row_mask:0xf bank_mask:0xf
	v_mov_b32_dpp v116, v62 row_shr:1 row_mask:0xf bank_mask:0xf
	v_mov_b32_dpp v118, v62 row_shr:2 row_mask:0xf bank_mask:0xf
	v_mov_b32_dpp v80, v58 row_shr:1 row_mask:0xf bank_mask:0xf
	v_mov_b32_dpp v82, v58 row_shr:2 row_mask:0xf bank_mask:0xf
	v_mov_b32_dpp v117, v63 row_shr:1 row_mask:0xf bank_mask:0xf
	v_mov_b32_dpp v119, v63 row_shr:2 row_mask:0xf bank_mask:0xf
	v_mov_b32_dpp v81, v59 row_shr:1 row_mask:0xf bank_mask:0xf
	v_mov_b32_dpp v83, v59 row_shr:2 row_mask:0xf bank_mask:0xf
	v_mov_b32_dpp v124, v52 row_shr:1 row_mask:0xf bank_mask:0xf
	v_mov_b32_dpp v126, v52 row_shr:2 row_mask:0xf bank_mask:0xf
	v_mov_b32_dpp v120, v48 row_shr:1 row_mask:0xf bank_mask:0xf
	v_mov_b32_dpp v122, v48 row_shr:2 row_mask:0xf bank_mask:0xf
	v_mov_b32_dpp v125, v53 row_shr:1 row_mask:0xf bank_mask:0xf
	v_mov_b32_dpp v127, v53 row_shr:2 row_mask:0xf bank_mask:0xf
	v_mov_b32_dpp v121, v49 row_shr:1 row_mask:0xf bank_mask:0xf
	v_mov_b32_dpp v123, v49 row_shr:2 row_mask:0xf bank_mask:0xf
	v_mov_b32_dpp v76, v54 row_shr:1 row_mask:0xf bank_mask:0xf
	v_mov_b32_dpp v78, v54 row_shr:2 row_mask:0xf bank_mask:0xf
	v_mov_b32_dpp v64, v50 row_shr:1 row_mask:0xf bank_mask:0xf
	v_mov_b32_dpp v66, v50 row_shr:2 row_mask:0xf bank_mask:0xf
	v_mov_b32_dpp v77, v55 row_shr:1 row_mask:0xf bank_mask:0xf
	v_mov_b32_dpp v79, v55 row_shr:2 row_mask:0xf bank_mask:0xf
	v_mov_b32_dpp v65, v51 row_shr:1 row_mask:0xf bank_mask:0xf
	v_mov_b32_dpp v67, v51 row_shr:2 row_mask:0xf bank_mask:0xf
	s_and_saveexec_b64 s[8:9], s[6:7]
	s_cbranch_execz .LBB0_1470
; __device__ __forceinline__ unsigned pk2(float lo, float hi) { const f32x2 v = {lo, hi}; return __builtin_bit_cast(unsigned, __builtin_convertvector(v, bf16x2_t)); }
; __device__ __forceinline__ float silu(float x) { return x * __builtin_amdgcn_rcpf(1.f + __builtin_amdgcn_exp2f(-1.4426950408889634f * x)); }
;     __device__ __forceinline__ void operator()(f32x4 (&acc)[2][2][4][2], const Unit& u, int, int, int, int) const {
;     ...
;                     for (int e = 0; e < 4; ++e) { const float A = acc[ai][0][m][n][e], Gv = acc[ai][1][m][n][e];
;                         const float Ap = m > 0 ? acc[ai][0][m > 0 ? m - 1 : 0][n][e] : 0.f, Gp = m > 0 ? acc[ai][1][m > 0 ? m - 1 : 0][n][e] : 0.f;
;                         const float a1 = dpp_prev(A, Ap, 1), a2 = dpp_prev(A, Ap, 2), g1 = dpp_prev(Gv, Gp, 1), g2 = dpp_prev(Gv, Gp, 2);
;                         const float ca = ba[n][e] + wa0[n][e] * a2 + wa1[n][e] * a1 + wa2[n][e] * A, cg = bg[n][e] + wg0[n][e] * g2 + wg1[n][e] * g1 + wg2[n][e] * Gv;
;                         r[4 * n + e] = silu(ca) * cg; }
;                 if (!(m == 0 && fr < 2)) { u32x4 w; w.x = pk2(r[0], r[1]); w.y = pk2(r[2], r[3]); w.z = pk2(r[4], r[5]); w.w = pk2(r[6], r[7]);
;                     *(u32x4*)(ACT + (size_t)(rowt + ai * HALF + m * 16) * NFF + f0) = w; }
	v_pk_fma_f32 v[126:127], v[100:101], v[126:127], v[112:113]
	v_pk_fma_f32 v[118:119], v[154:155], v[118:119], v[158:159]
	v_pk_fma_f32 v[124:125], v[108:109], v[124:125], v[126:127]
	v_pk_fma_f32 v[116:117], v[150:151], v[116:117], v[118:119]
	v_pk_fma_f32 v[124:125], v[52:53], v[104:105], v[124:125]
	v_pk_fma_f32 v[116:117], v[62:63], v[146:147], v[116:117]
	v_mul_f32_e32 v126, 0xbfb8aa3b, v124
	v_mul_f32_e32 v127, 0xbfb8aa3b, v125
	v_exp_f32_e32 v126, v126
	v_exp_f32_e32 v127, v127
	v_pk_fma_f32 v[122:123], v[84:85], v[122:123], v[96:97]
	v_mul_f32_e32 v118, 0xbfb8aa3b, v116
	v_add_f32_e32 v126, 1.0, v126
	v_add_f32_e32 v127, 1.0, v127
	v_rcp_f32_e32 v126, v126
	v_rcp_f32_e32 v127, v127
	v_pk_fma_f32 v[120:121], v[88:89], v[120:121], v[122:123]
	v_pk_fma_f32 v[74:75], v[152:153], v[74:75], v[156:157]
	v_pk_fma_f32 v[120:121], v[48:49], v[92:93], v[120:121]
	v_pk_mul_f32 v[122:123], v[124:125], v[126:127]
	v_exp_f32_e32 v124, v118
	v_mul_f32_e32 v118, 0xbfb8aa3b, v117
	v_exp_f32_e32 v125, v118
	v_pk_mul_f32 v[118:119], v[120:121], v[122:123]
	v_add_f32_e32 v120, 1.0, v124
	v_rcp_f32_e32 v120, v120
	v_add_f32_e32 v121, 1.0, v125
	v_rcp_f32_e32 v121, v121
	v_pk_fma_f32 v[72:73], v[148:149], v[72:73], v[74:75]
	v_pk_fma_f32 v[82:83], v[130:131], v[82:83], v[142:143]
	v_pk_fma_f32 v[72:73], v[60:61], v[144:145], v[72:73]
	v_pk_fma_f32 v[80:81], v[134:135], v[80:81], v[82:83]
	v_mul_f32_e32 v74, 0xbfb8aa3b, v72
	v_pk_mul_f32 v[82:83], v[116:117], v[120:121]
	v_exp_f32_e32 v116, v74
	v_mul_f32_e32 v74, 0xbfb8aa3b, v73
	v_exp_f32_e32 v117, v74
	v_pk_fma_f32 v[80:81], v[58:59], v[138:139], v[80:81]
	v_pk_fma_f32 v[70:71], v[128:129], v[70:71], v[140:141]
	v_pk_mul_f32 v[74:75], v[80:81], v[82:83]
	v_add_f32_e32 v80, 1.0, v116
	v_add_f32_e32 v81, 1.0, v117
	v_rcp_f32_e32 v80, v80
	v_rcp_f32_e32 v81, v81
	v_pk_fma_f32 v[68:69], v[132:133], v[68:69], v[70:71]
	v_pk_fma_f32 v[66:67], v[86:87], v[66:67], v[98:99]
	v_pk_fma_f32 v[68:69], v[56:57], v[136:137], v[68:69]
	v_pk_mul_f32 v[70:71], v[72:73], v[80:81]
	v_pk_fma_f32 v[72:73], v[102:103], v[78:79], v[114:115]
	v_pk_mul_f32 v[68:69], v[68:69], v[70:71]
	v_pk_fma_f32 v[72:73], v[110:111], v[76:77], v[72:73]
	v_pk_fma_f32 v[64:65], v[90:91], v[64:65], v[66:67]
	v_pk_fma_f32 v[72:73], v[54:55], v[106:107], v[72:73]
	v_pk_fma_f32 v[64:65], v[50:51], v[94:95], v[64:65]
	v_mul_f32_e32 v76, 0xbfb8aa3b, v72
	v_mul_f32_e32 v77, 0xbfb8aa3b, v73
	v_exp_f32_e32 v76, v76
	v_exp_f32_e32 v77, v77
	v_add_f32_e32 v70, 1.0, v76
	v_add_f32_e32 v71, 1.0, v77
	v_rcp_f32_e32 v70, v70
	v_rcp_f32_e32 v71, v71
	s_nop 0
	v_pk_mul_f32 v[66:67], v[72:73], v[70:71]
	s_nop 0
	v_pk_mul_f32 v[70:71], v[64:65], v[66:67]
	v_cvt_pk_bf16_f32 v64, v68, v69
	v_mov_b64_e32 v[68:69], s[20:21]
	v_mad_i64_i32 v[68:69], s[6:7], v247, s83, v[68:69]
	v_cvt_pk_bf16_f32 v65, v74, v75
	v_cvt_pk_bf16_f32 v66, v118, v119
	v_cvt_pk_bf16_f32 v67, v70, v71
	v_lshl_add_u64 v[68:69], v[208:209], 1, v[68:69]
	global_store_dwordx4 v[68:69], v[64:67], off
